# LayerNorm sample rows: gamma/beta for all column chunks loaded once after the plane sums (was one pair per chunk behind its own vmcnt(0))
# speedup vs baseline: 1.0098x; 1.0005x over previous
.LBB0_303:
	global_load_dwordx4 v[140:143], v[44:45], off
	global_load_dwordx4 v[144:147], v[46:47], off
	global_load_dwordx4 v[148:151], v[44:45], off offset:1024
	global_load_dwordx4 v[152:155], v[46:47], off offset:1024
	global_load_dwordx4 v[156:159], v[44:45], off offset:2048
	global_load_dwordx4 v[160:163], v[46:47], off offset:2048
	global_load_dwordx4 v[164:167], v[44:45], off offset:3072
	global_load_dwordx4 v[168:171], v[46:47], off offset:3072
	global_load_dwordx4 v[172:175], v[48:49], off
	global_load_dwordx4 v[176:179], v[50:51], off
	global_load_dwordx4 v[180:183], v[54:55], off
	global_load_dwordx4 v[184:187], v[56:57], off
	global_load_dwordx4 v[188:191], v[58:59], off
	global_load_dwordx4 v[192:195], v[60:61], off
	global_load_dwordx4 v[196:199], v[64:65], off
	global_load_dwordx4 v[220:223], v[66:67], off
	s_waitcnt vmcnt(0)
	v_mov_b32_e32 v74, v26
	v_mov_b32_e32 v75, v30
	v_mov_b32_e32 v76, v27
	v_mov_b32_e32 v77, v31
	v_pk_add_f32 v[74:75], v[74:75], v[76:77]
	v_mov_b32_e32 v76, v28
	v_mov_b32_e32 v77, v32
	v_mov_b32_e32 v78, v29
	v_mov_b32_e32 v79, v33
	v_pk_add_f32 v[76:77], v[76:77], v[78:79]
	v_mov_b32_e32 v78, v22
	v_pk_add_f32 v[74:75], v[74:75], v[76:77]
	v_mov_b32_e32 v76, v23
	v_mov_b32_e32 v77, v24
	v_mov_b32_e32 v79, v25
	v_pk_add_f32 v[76:77], v[76:77], v[78:79]
	v_add_f32_e32 v35, 0, v75
	v_pk_add_f32 v[76:77], v[76:77], v[76:77] op_sel_hi:[0,1]
	v_add_f32_e32 v75, v74, v35
	v_add_f32_e32 v79, v2, v3
	v_add_f32_e32 v81, v4, v5
	v_mov_b32_e32 v78, v14
	v_mov_b32_e32 v80, v15
	v_mov_b32_e32 v76, v16
	v_mov_b32_e32 v74, v17
	v_pk_add_f32 v[78:79], v[78:79], v[80:81]
	v_pk_add_f32 v[74:75], v[76:77], v[74:75]
	v_mov_b32_e32 v76, v7
	v_pk_add_f32 v[74:75], v[78:79], v[74:75]
	v_mov_b32_e32 v77, v8
	v_mov_b32_e32 v78, v6
	v_mov_b32_e32 v79, v9
	v_pk_add_f32 v[76:77], v[76:77], v[78:79]
	v_pk_add_f32 v[74:75], v[74:75], v[74:75] op_sel_hi:[0,1]
	v_pk_add_f32 v[76:77], v[76:77], v[76:77] op_sel_hi:[0,1]
	v_mov_b32_e32 v34, v21
	v_mov_b32_e32 v36, v20
	v_mov_b32_e32 v38, v19
	v_mov_b32_e32 v40, v18
	v_add_f32_e32 v41, v10, v11
	v_add_f32_e32 v39, v12, v13
	v_mov_b32_e32 v37, v77
	v_mov_b32_e32 v35, v75
	v_pk_add_f32 v[38:39], v[40:41], v[38:39]
	v_pk_add_f32 v[34:35], v[36:37], v[34:35]
	s_add_u32 s2, s92, s30
	v_pk_add_f32 v[34:35], v[38:39], v[34:35]
	s_addc_u32 s3, s93, s31
	v_add_f32_e32 v34, v34, v35
	v_mov_b32_e32 v73, v1
	s_nop 0
	v_add_f32_dpp v34, v34, v34 quad_perm:[1,0,3,2] row_mask:0xf bank_mask:0xf bound_ctrl:1
	s_nop 1
	v_add_f32_dpp v34, v34, v34 quad_perm:[2,3,0,1] row_mask:0xf bank_mask:0xf bound_ctrl:1
	s_nop 1
	v_add_f32_dpp v34, v34, v34 row_half_mirror row_mask:0xf bank_mask:0xf bound_ctrl:1
	s_nop 1
	v_add_f32_dpp v34, v34, v34 row_ror:8 row_mask:0xf bank_mask:0xf bound_ctrl:1
	s_nop 0
	v_readlane_b32 s18, v34, 16
	v_readlane_b32 s27, v34, 48
	v_readlane_b32 s30, v34, 0
	v_readlane_b32 s31, v34, 32
	v_mov_b32_e32 v34, s18
	v_mov_b32_e32 v35, s27
	v_pk_add_f32 v[34:35], s[30:31], v[34:35]
	s_nop 0
	v_add_f32_e32 v63, v34, v35
	v_fmac_f32_e32 v31, 0xba000000, v63
	v_fmac_f32_e32 v27, 0xba000000, v63
	v_fmac_f32_e32 v33, 0xba000000, v63
	v_fmac_f32_e32 v30, 0xba000000, v63
	v_fmac_f32_e32 v29, 0xba000000, v63
	v_fmac_f32_e32 v26, 0xba000000, v63
	v_mov_b32_e32 v36, v31
	v_mov_b32_e32 v37, v27
	v_fmac_f32_e32 v32, 0xba000000, v63
	v_fmac_f32_e32 v28, 0xba000000, v63
	v_mov_b32_e32 v34, v30
	v_mov_b32_e32 v35, v26
	v_pk_mul_f32 v[36:37], v[36:37], v[36:37]
	v_mov_b32_e32 v38, v33
	v_mov_b32_e32 v39, v29
	v_pk_fma_f32 v[34:35], v[34:35], v[34:35], v[36:37]
	v_mov_b32_e32 v36, v32
	v_mov_b32_e32 v37, v28
	v_pk_mul_f32 v[38:39], v[38:39], v[38:39]
	v_fmac_f32_e32 v25, 0xba000000, v63
	v_pk_fma_f32 v[36:37], v[36:37], v[36:37], v[38:39]
	v_fmac_f32_e32 v24, 0xba000000, v63
	v_pk_add_f32 v[34:35], v[34:35], v[36:37]
	v_fmac_f32_e32 v23, 0xba000000, v63
	v_fmac_f32_e32 v22, 0xba000000, v63
	v_pk_add_f32 v[34:35], v[34:35], v[34:35] op_sel_hi:[0,1]
	v_pk_mul_f32 v[36:37], v[24:25], v[24:25]
	v_pk_mul_f32 v[38:39], v[22:23], v[22:23]
	v_fmac_f32_e32 v2, 0xba000000, v63
	v_pk_mov_b32 v[40:41], v[38:39], v[36:37] op_sel:[1,0]
	v_mov_b32_e32 v39, v37
	v_fmac_f32_e32 v4, 0xba000000, v63
	v_fmac_f32_e32 v3, 0xba000000, v63
	v_mul_f32_e32 v34, v2, v2
	v_pk_add_f32 v[36:37], v[40:41], v[38:39]
	v_fmac_f32_e32 v5, 0xba000000, v63
	v_pk_fma_f32 v[38:39], v[2:3], v[2:3], v[34:35] op_sel_hi:[1,1,0]
	v_mul_f32_e32 v34, v4, v4
	v_pk_add_f32 v[36:37], v[36:37], v[36:37] op_sel_hi:[0,1]
	v_pk_fma_f32 v[40:41], v[4:5], v[4:5], v[34:35] op_sel_hi:[1,1,0]
	v_fmac_f32_e32 v17, 0xba000000, v63
	v_fmac_f32_e32 v16, 0xba000000, v63
	v_fmac_f32_e32 v15, 0xba000000, v63
	v_fmac_f32_e32 v14, 0xba000000, v63
	v_mul_f32_e32 v38, v14, v14
	v_mul_f32_e32 v40, v15, v15
	v_mul_f32_e32 v36, v16, v16
	v_mul_f32_e32 v34, v17, v17
	v_pk_add_f32 v[38:39], v[38:39], v[40:41]
	v_pk_add_f32 v[34:35], v[36:37], v[34:35]
	v_fmac_f32_e32 v9, 0xba000000, v63
	v_pk_add_f32 v[34:35], v[38:39], v[34:35]
	v_fmac_f32_e32 v8, 0xba000000, v63
	v_fmac_f32_e32 v7, 0xba000000, v63
	v_fmac_f32_e32 v6, 0xba000000, v63
	v_pk_add_f32 v[34:35], v[34:35], v[34:35] op_sel_hi:[0,1]
	v_pk_mul_f32 v[36:37], v[8:9], v[8:9]
	v_pk_mul_f32 v[38:39], v[6:7], v[6:7]
	v_fmac_f32_e32 v10, 0xba000000, v63
	v_pk_mov_b32 v[40:41], v[38:39], v[36:37] op_sel:[1,0]
	v_mov_b32_e32 v39, v37
	v_fmac_f32_e32 v12, 0xba000000, v63
	v_fmac_f32_e32 v11, 0xba000000, v63
	v_mul_f32_e32 v34, v10, v10
	v_pk_add_f32 v[36:37], v[40:41], v[38:39]
	v_fmac_f32_e32 v13, 0xba000000, v63
	v_pk_fma_f32 v[38:39], v[10:11], v[10:11], v[34:35] op_sel_hi:[1,1,0]
	v_mul_f32_e32 v34, v12, v12
	v_pk_add_f32 v[36:37], v[36:37], v[36:37] op_sel_hi:[0,1]
	v_pk_fma_f32 v[40:41], v[12:13], v[12:13], v[34:35] op_sel_hi:[1,1,0]
	v_fmamk_f32 v75, v63, 0xba000000, v21
	v_fmamk_f32 v74, v63, 0xba000000, v20
	v_fmamk_f32 v19, v63, 0xba000000, v19
	v_fmac_f32_e32 v18, 0xba000000, v63
	v_mul_f32_e32 v38, v18, v18
	v_mul_f32_e32 v40, v19, v19
	v_mul_f32_e32 v36, v74, v74
	v_mul_f32_e32 v34, v75, v75
	v_pk_add_f32 v[20:21], v[38:39], v[40:41]
	v_pk_add_f32 v[34:35], v[36:37], v[34:35]
	s_nop 0
	v_pk_add_f32 v[20:21], v[20:21], v[34:35]
	s_nop 1
	v_mov_b64_e32 v[34:35], v[140:141]
	v_mov_b64_e32 v[36:37], v[142:143]
	s_nop 1
	v_mov_b64_e32 v[38:39], v[144:145]
	v_mov_b64_e32 v[40:41], v[146:147]
	v_add_f32_e32 v20, v20, v21
	s_nop 1
	v_add_f32_dpp v20, v20, v20 quad_perm:[1,0,3,2] row_mask:0xf bank_mask:0xf bound_ctrl:1
	s_nop 1
	v_add_f32_dpp v20, v20, v20 quad_perm:[2,3,0,1] row_mask:0xf bank_mask:0xf bound_ctrl:1
	s_nop 1
	v_add_f32_dpp v20, v20, v20 row_half_mirror row_mask:0xf bank_mask:0xf bound_ctrl:1
	s_nop 1
	v_add_f32_dpp v20, v20, v20 row_ror:8 row_mask:0xf bank_mask:0xf bound_ctrl:1
	s_nop 0
	v_readlane_b32 s18, v20, 16
	v_readlane_b32 s27, v20, 48
	v_readlane_b32 s30, v20, 0
	v_readlane_b32 s31, v20, 32
	v_mov_b32_e32 v20, s18
	v_mov_b32_e32 v21, s27
	v_pk_add_f32 v[20:21], s[30:31], v[20:21]
	s_and_b64 s[30:31], s[16:17], exec
	v_add_f32_e32 v20, v20, v21
	v_fmamk_f32 v20, v20, 0x3a000000, v203
	v_rsq_f32_e32 v76, v20
	s_cselect_b32 s3, 0, s3
	s_cselect_b32 s2, 0, s2
	v_lshl_add_u64 v[78:79], s[2:3], 0, v[0:1]
	v_pk_mul_f32 v[20:21], v[30:31], v[76:77] op_sel_hi:[1,0]
	v_pk_mul_f32 v[30:31], v[32:33], v[76:77] op_sel_hi:[1,0]
	v_mov_b32_e32 v80, v76
	v_mov_b32_e32 v81, v76
	s_mov_b64 s[30:31], -1
	s_andn2_b64 vcc, exec, s[22:23]
	s_nop 0
	v_pk_fma_f32 v[32:33], v[36:37], v[30:31], v[40:41]
	v_pk_fma_f32 v[30:31], v[34:35], v[20:21], v[38:39]
	v_cndmask_b32_e64 v20, 0, 1, s[22:23]
	v_lshl_add_u64 v[34:35], s[24:25], 0, v[72:73]
	v_cmp_ne_u32_e64 s[2:3], 1, v20
	v_pk_mul_f32 v[20:21], v[26:27], v[80:81]
	global_store_dwordx4 v72, v[30:33], s[24:25]
	s_cbranch_vccnz .LBB0_305
	v_bfe_u32 v26, v30, 16, 1
	v_add3_u32 v26, v30, v26, s60
	v_bfe_u32 v27, v31, 16, 1
	v_lshrrev_b32_e32 v26, 16, v26
	v_add3_u32 v27, v31, v27, s60
	v_and_or_b32 v26, v27, s33, v26
	v_bfe_u32 v27, v32, 16, 1
	v_add3_u32 v27, v32, v27, s60
	v_bfe_u32 v30, v33, 16, 1
	v_lshrrev_b32_e32 v27, 16, v27
	v_add3_u32 v30, v33, v30, s60
	v_and_or_b32 v27, v30, s33, v27
	global_store_dwordx2 v[78:79], v[26:27], off
	s_nop 1
	v_mov_b64_e32 v[30:31], v[148:149]
	v_mov_b64_e32 v[32:33], v[150:151]
	s_nop 1
	v_mov_b64_e32 v[36:37], v[152:153]
	v_mov_b64_e32 v[38:39], v[154:155]
	v_mov_b32_e32 v77, v76
	v_pk_mul_f32 v[26:27], v[28:29], v[76:77]
	s_mov_b64 s[30:31], 0
	s_nop 0
	v_pk_fma_f32 v[32:33], v[26:27], v[32:33], v[38:39]
	v_pk_fma_f32 v[30:31], v[20:21], v[30:31], v[36:37]
	v_bfe_u32 v36, v32, 16, 1
	v_bfe_u32 v26, v30, 16, 1
	global_store_dwordx4 v[34:35], v[30:33], off offset:1024
	v_bfe_u32 v27, v31, 16, 1
	v_bfe_u32 v37, v33, 16, 1
	v_add3_u32 v26, v30, v26, s60
	v_add3_u32 v30, v32, v36, s60
	v_add3_u32 v27, v31, v27, s60
	v_add3_u32 v31, v33, v37, s60
	v_lshrrev_b32_e32 v26, 16, v26
	v_lshrrev_b32_e32 v30, 16, v30
	v_and_or_b32 v26, v27, s33, v26
	v_and_or_b32 v27, v31, s33, v30
	global_store_dwordx2 v[78:79], v[26:27], off offset:512
.LBB0_305:
	s_andn2_b64 vcc, exec, s[30:31]
	s_cbranch_vccnz .LBB0_307
	s_nop 1
	v_mov_b64_e32 v[30:31], v[148:149]
	v_mov_b64_e32 v[32:33], v[150:151]
	s_nop 1
	v_mov_b64_e32 v[36:37], v[152:153]
	v_mov_b64_e32 v[38:39], v[154:155]
	v_mov_b32_e32 v77, v76
	v_pk_mul_f32 v[26:27], v[28:29], v[76:77]
	s_nop 0
	v_pk_fma_f32 v[28:29], v[26:27], v[32:33], v[38:39]
	v_pk_fma_f32 v[26:27], v[20:21], v[30:31], v[36:37]
	global_store_dwordx4 v[34:35], v[26:29], off offset:1024
.LBB0_307:
	s_nop 1
	v_mov_b64_e32 v[26:27], v[156:157]
	v_mov_b64_e32 v[28:29], v[158:159]
	s_nop 0
	s_nop 1
	v_mov_b64_e32 v[30:31], v[160:161]
	v_mov_b64_e32 v[32:33], v[162:163]
	v_mov_b32_e32 v77, v76
	v_pk_mul_f32 v[20:21], v[22:23], v[80:81]
	v_pk_mul_f32 v[22:23], v[24:25], v[76:77]
	s_mov_b64 s[30:31], -1
	s_and_b64 vcc, exec, s[2:3]
	v_pk_mul_f32 v[2:3], v[2:3], v[80:81]
	s_nop 0
	v_pk_fma_f32 v[22:23], v[22:23], v[28:29], v[32:33]
	v_pk_fma_f32 v[20:21], v[20:21], v[26:27], v[30:31]
	global_store_dwordx4 v[34:35], v[20:23], off offset:2048
	s_cbranch_vccnz .LBB0_309
	v_bfe_u32 v24, v20, 16, 1
	v_add3_u32 v20, v20, v24, s60
	v_bfe_u32 v24, v21, 16, 1
	v_lshrrev_b32_e32 v20, 16, v20
	v_add3_u32 v21, v21, v24, s60
	v_and_or_b32 v20, v21, s33, v20
	v_bfe_u32 v21, v22, 16, 1
	v_add3_u32 v21, v22, v21, s60
	v_bfe_u32 v22, v23, 16, 1
	v_lshrrev_b32_e32 v21, 16, v21
	v_add3_u32 v22, v23, v22, s60
	v_and_or_b32 v21, v22, s33, v21
	global_store_dwordx2 v[78:79], v[20:21], off offset:1024
	s_nop 1
	v_mov_b64_e32 v[20:21], v[164:165]
	v_mov_b64_e32 v[22:23], v[166:167]
	s_nop 0
	s_nop 1
	v_mov_b64_e32 v[24:25], v[168:169]
	v_mov_b64_e32 v[26:27], v[170:171]
	v_pk_mul_f32 v[28:29], v[4:5], v[76:77]
	s_mov_b64 s[30:31], 0
	s_nop 0
	v_pk_fma_f32 v[22:23], v[28:29], v[22:23], v[26:27]
	v_pk_fma_f32 v[20:21], v[2:3], v[20:21], v[24:25]
	v_bfe_u32 v26, v22, 16, 1
	v_bfe_u32 v24, v20, 16, 1
	global_store_dwordx4 v[34:35], v[20:23], off offset:3072
	v_bfe_u32 v25, v21, 16, 1
	v_bfe_u32 v27, v23, 16, 1
	v_add3_u32 v20, v20, v24, s60
	v_add3_u32 v22, v22, v26, s60
	v_add3_u32 v21, v21, v25, s60
	v_add3_u32 v23, v23, v27, s60
	v_lshrrev_b32_e32 v20, 16, v20
	v_lshrrev_b32_e32 v22, 16, v22
	v_and_or_b32 v20, v21, s33, v20
	v_and_or_b32 v21, v23, s33, v22
	global_store_dwordx2 v[78:79], v[20:21], off offset:1536
.LBB0_309:
	s_andn2_b64 vcc, exec, s[30:31]
	s_cbranch_vccnz .LBB0_311
	s_nop 1
	v_mov_b64_e32 v[20:21], v[164:165]
	v_mov_b64_e32 v[22:23], v[166:167]
	s_nop 1
	v_mov_b64_e32 v[24:25], v[168:169]
	v_mov_b64_e32 v[26:27], v[170:171]
	v_mov_b32_e32 v77, v76
	v_pk_mul_f32 v[4:5], v[4:5], v[76:77]
	s_nop 0
	v_pk_fma_f32 v[2:3], v[2:3], v[20:21], v[24:25]
	v_pk_fma_f32 v[4:5], v[4:5], v[22:23], v[26:27]
	global_store_dwordx4 v[34:35], v[2:5], off offset:3072
.LBB0_311:
	s_nop 1
	v_mov_b64_e32 v[2:3], v[172:173]
	v_mov_b64_e32 v[4:5], v[174:175]
	s_nop 0
	s_nop 1
	v_mov_b64_e32 v[20:21], v[176:177]
	v_mov_b64_e32 v[22:23], v[178:179]
	v_mov_b32_e32 v77, v76
	v_pk_mul_f32 v[16:17], v[16:17], v[76:77]
	v_pk_mul_f32 v[14:15], v[14:15], v[80:81]
	s_mov_b64 s[30:31], -1
	s_and_b64 vcc, exec, s[2:3]
	v_pk_mul_f32 v[6:7], v[6:7], v[80:81]
	s_nop 0
	v_pk_fma_f32 v[4:5], v[16:17], v[4:5], v[22:23]
	v_pk_fma_f32 v[2:3], v[14:15], v[2:3], v[20:21]
	v_lshlrev_b32_e32 v14, 2, v52
	global_store_dwordx4 v43, v[2:5], s[24:25]
	s_cbranch_vccnz .LBB0_313
	v_bfe_u32 v15, v2, 16, 1
	v_add3_u32 v2, v2, v15, s60
	v_bfe_u32 v15, v3, 16, 1
	v_lshrrev_b32_e32 v2, 16, v2
	v_add3_u32 v3, v3, v15, s60
	v_and_or_b32 v2, v3, s33, v2
	v_bfe_u32 v3, v4, 16, 1
	v_add3_u32 v3, v4, v3, s60
	v_bfe_u32 v4, v5, 16, 1
	v_lshrrev_b32_e32 v3, 16, v3
	v_add3_u32 v4, v5, v4, s60
	v_and_or_b32 v3, v4, s33, v3
	global_store_dwordx2 v[78:79], v[2:3], off offset:2048
	s_nop 1
	v_mov_b64_e32 v[2:3], v[180:181]
	v_mov_b64_e32 v[4:5], v[182:183]
	s_nop 0
	s_nop 1
	v_mov_b64_e32 v[20:21], v[184:185]
	v_mov_b64_e32 v[22:23], v[186:187]
	v_pk_mul_f32 v[16:17], v[8:9], v[76:77]
	s_mov_b64 s[30:31], 0
	s_nop 0
	v_pk_fma_f32 v[4:5], v[16:17], v[4:5], v[22:23]
	v_pk_fma_f32 v[2:3], v[6:7], v[2:3], v[20:21]
	v_bfe_u32 v17, v4, 16, 1
	v_bfe_u32 v15, v2, 16, 1
	global_store_dwordx4 v14, v[2:5], s[24:25]
	v_bfe_u32 v16, v3, 16, 1
	v_bfe_u32 v20, v5, 16, 1
	v_add3_u32 v2, v2, v15, s60
	v_add3_u32 v4, v4, v17, s60
	v_add3_u32 v3, v3, v16, s60
	v_add3_u32 v5, v5, v20, s60
	v_lshrrev_b32_e32 v2, 16, v2
	v_lshrrev_b32_e32 v4, 16, v4
	v_and_or_b32 v2, v3, s33, v2
	v_and_or_b32 v3, v5, s33, v4
	global_store_dwordx2 v[78:79], v[2:3], off offset:2560
.LBB0_313:
	s_andn2_b64 vcc, exec, s[30:31]
	s_cbranch_vccnz .LBB0_315
	s_nop 1
	v_mov_b64_e32 v[2:3], v[180:181]
	v_mov_b64_e32 v[4:5], v[182:183]
	s_nop 1
	v_mov_b64_e32 v[20:21], v[184:185]
	v_mov_b64_e32 v[22:23], v[186:187]
	v_mov_b32_e32 v77, v76
	v_pk_mul_f32 v[8:9], v[8:9], v[76:77]
	s_nop 0
	v_pk_fma_f32 v[2:3], v[6:7], v[2:3], v[20:21]
	v_pk_fma_f32 v[4:5], v[8:9], v[4:5], v[22:23]
	global_store_dwordx4 v14, v[2:5], s[24:25]
.LBB0_315:
	s_nop 1
	v_mov_b64_e32 v[2:3], v[188:189]
	v_mov_b64_e32 v[4:5], v[190:191]
	s_nop 0
	s_nop 1
	v_mov_b64_e32 v[14:15], v[192:193]
	v_mov_b64_e32 v[16:17], v[194:195]
	v_mov_b32_e32 v77, v76
	v_pk_mul_f32 v[8:9], v[10:11], v[80:81]
	v_pk_mul_f32 v[10:11], v[12:13], v[76:77]
	s_mov_b64 s[30:31], -1
	s_and_b64 vcc, exec, s[2:3]
	v_pk_mul_f32 v[6:7], v[18:19], v[80:81]
	s_nop 0
	v_pk_fma_f32 v[4:5], v[10:11], v[4:5], v[16:17]
	v_pk_fma_f32 v[2:3], v[8:9], v[2:3], v[14:15]
	v_lshlrev_b32_e32 v8, 2, v62
	global_store_dwordx4 v53, v[2:5], s[24:25]
	s_cbranch_vccnz .LBB0_317
	v_bfe_u32 v9, v2, 16, 1
	v_add3_u32 v2, v2, v9, s60
	v_bfe_u32 v9, v3, 16, 1
	v_lshrrev_b32_e32 v2, 16, v2
	v_add3_u32 v3, v3, v9, s60
	v_and_or_b32 v2, v3, s33, v2
	v_bfe_u32 v3, v4, 16, 1
	v_add3_u32 v3, v4, v3, s60
	v_bfe_u32 v4, v5, 16, 1
	v_lshrrev_b32_e32 v3, 16, v3
	v_add3_u32 v4, v5, v4, s60
	v_and_or_b32 v3, v4, s33, v3
	global_store_dwordx2 v[78:79], v[2:3], off offset:3072
	s_nop 1
	v_mov_b64_e32 v[2:3], v[196:197]
	v_mov_b64_e32 v[4:5], v[198:199]
	s_nop 0
	s_nop 1
	v_mov_b64_e32 v[10:11], v[220:221]
	v_mov_b64_e32 v[12:13], v[222:223]
	v_pk_mul_f32 v[14:15], v[74:75], v[76:77]
	s_nop 0
	v_pk_fma_f32 v[4:5], v[14:15], v[4:5], v[12:13]
	v_pk_fma_f32 v[2:3], v[6:7], v[2:3], v[10:11]
	v_bfe_u32 v11, v4, 16, 1
	v_bfe_u32 v9, v2, 16, 1
	global_store_dwordx4 v8, v[2:5], s[24:25]
	v_bfe_u32 v10, v3, 16, 1
	v_bfe_u32 v12, v5, 16, 1
	v_add3_u32 v2, v2, v9, s60
	v_add3_u32 v4, v4, v11, s60
	v_add3_u32 v3, v3, v10, s60
	v_add3_u32 v5, v5, v12, s60
	v_lshrrev_b32_e32 v2, 16, v2
	v_lshrrev_b32_e32 v4, 16, v4
	v_and_or_b32 v2, v3, s33, v2
	v_and_or_b32 v3, v5, s33, v4
	global_store_dwordx2 v[78:79], v[2:3], off offset:3584
	s_cbranch_execnz .LBB0_256
	s_branch .LBB0_318

.LBB0_318:
	s_nop 1
	v_mov_b64_e32 v[2:3], v[196:197]
	v_mov_b64_e32 v[4:5], v[198:199]
	s_nop 1
	v_mov_b64_e32 v[10:11], v[220:221]
	v_mov_b64_e32 v[12:13], v[222:223]
	v_mov_b32_e32 v77, v76
	v_pk_mul_f32 v[14:15], v[74:75], v[76:77]
	s_nop 0
	v_pk_fma_f32 v[2:3], v[6:7], v[2:3], v[10:11]
	v_pk_fma_f32 v[4:5], v[14:15], v[4:5], v[12:13]
	global_store_dwordx4 v8, v[2:5], s[24:25]
	s_branch .LBB0_256
